# prologue de-serialisation: all 14 prologue LDS-DMA loads of each GEMM phase issue together (dropped the wait+barrier between tile 0 and tile 1)
# baseline (speedup 1.0000x reference)
; #define PG8_STAGE(bufoff, gbase, voff) do { _Pragma("unroll") for (int _i = 0; _i < 2; ++_i) \
;         __builtin_amdgcn_global_load_lds((const unsigned*)((const char*)(gbase) + (voff)[_i]), (LAS unsigned*)(lds + (bufoff) + ldsw + _i * 8192), 16, 0, 0); } while (0)
; #define PG8_WAIT_V(n) asm volatile("s_waitcnt vmcnt(" #n ")" ::: "memory")
; #define PG8_BAR __builtin_amdgcn_s_barrier()
; template <class Epi>
; __device__ __forceinline__ void gemm_phase(LAS unsigned char* lds, const Gemm g, const Sched& S, const Epi& E) {
;     ...
;     PG8_STAGE(PG8_SB(0, 0), cB, voffB); PG8_STAGE(PG8_SA(0, 0), cA, voffA); PG8_STAGE(PG8_SB(0, 1), cB + hstepB, voffB); PG8_STAGE(PG8_SA(0, 1), cA + hstepA, voffA);
;     if (wr == 1) PG8_BAR;
;     PG8_WAIT_V(4); PG8_BAR;
;     PG8_STAGE(PG8_SB(1, 0), cB + kstep, voffB); PG8_STAGE(PG8_SA(1, 0), cA + kstep, voffA); PG8_STAGE(PG8_SB(1, 1), cB + hstepB + kstep, voffB);
;     PG8_WAIT_V(6); PG8_BAR;
.LBB0_386:
	s_add_i32 m0, s42, 0x18000
	v_lshl_add_u64 v[2:3], v[2:3], 0, s[60:61]
	global_load_lds_dwordx4 v[2:3], off
	v_lshl_add_u64 v[2:3], v[4:5], 0, s[60:61]
	s_add_i32 m0, s42, 0x1a000
	s_add_i32 s67, s42, 0x8000
	global_load_lds_dwordx4 v[2:3], off
	v_lshl_add_u64 v[2:3], v[6:7], 0, s[60:61]
	s_mov_b32 m0, s67
	s_add_i32 s2, s42, 0xa000
	global_load_lds_dwordx4 v[2:3], off
	v_lshl_add_u64 v[2:3], v[8:9], 0, s[60:61]
	s_mov_b32 m0, s2
	v_bfe_u32 v20, v17, 4, 2
	global_load_lds_dwordx4 v[2:3], off
	s_add_i32 m0, s42, 0x1c000
	v_lshl_add_u64 v[2:3], v[10:11], 0, s[60:61]
	global_load_lds_dwordx4 v[2:3], off
	v_lshl_add_u64 v[2:3], v[12:13], 0, s[60:61]
	s_add_i32 m0, s42, 0x1e000
	v_and_b32_e32 v150, 15, v17
	global_load_lds_dwordx4 v[2:3], off
	v_lshlrev_b32_e32 v22, 4, v20
	v_lshlrev_b32_e32 v17, 2, v17
	s_and_b32 s3, s0, 3
	s_lshl_b32 s0, s1, 6
	v_lshl_or_b32 v22, v150, 6, v22
	s_lshl_b32 s1, s1, 13
	v_and_b32_e32 v17, 32, v17
	v_readlane_b32 s8, v253, 61
	v_bitop3_b32 v23, v22, s1, v17 bitop3:0xde
	s_lshl_b32 s1, s3, 12
	s_add_i32 s71, s73, -2
	v_readlane_b32 s9, v253, 62
	s_cmp_eq_u64 s[8:9], 0
	s_cselect_b64 s[80:81], -1, 0
	s_cmp_lg_u64 s[8:9], 0
	v_readlane_b32 s8, v254, 13
	s_cselect_b64 s[82:83], -1, 0
	s_ashr_i32 s40, s8, 31
	v_readlane_b32 s8, v253, 30
	s_lshr_b32 s8, s54, 3
	v_readlane_b32 s9, v253, 31
	v_writelane_b32 v254, s8, 47
	s_add_i32 s8, s8, 1
	v_writelane_b32 v254, s8, 31
	s_mov_b32 s27, s9
	v_readlane_b32 s8, v254, 5
	v_readlane_b32 s9, v254, 37
	s_mul_i32 s56, s8, s9
	v_cvt_f32_u32_e32 v3, s56
	v_or_b32_e32 v151, s0, v150
	v_lshlrev_b32_e32 v21, 3, v20
	v_and_b32_e32 v2, 63, v219
	v_rcp_iflag_f32_e32 v3, v3
	v_or_b32_e32 v153, s0, v2
	v_lshlrev_b32_e32 v154, 4, v151
	v_lshl_or_b32 v2, s3, 5, v21
	s_add_i32 s8, 0, 0x20000
	s_lshl_b32 s3, s3, 2
	s_add_i32 s51, s8, s3
	v_add_u32_e32 v155, s8, v154
	v_readlane_b32 s8, v253, 21
	v_mul_f32_e32 v3, 0x4f7ffffe, v3
	v_cvt_u32_f32_e32 v3, v3
	v_add_u32_e32 v157, s8, v154
	v_readlane_b32 s8, v253, 22
	v_add_u32_e32 v156, s3, v155
	v_add_u32_e32 v158, s3, v157
	v_add_u32_e32 v159, s8, v154
	v_readlane_b32 s8, v253, 23
	v_add_u32_e32 v160, s3, v159
	v_add_u32_e32 v0, v15, v0
	v_add_u32_e32 v161, s8, v154
	v_readlane_b32 s8, v253, 24
	v_add_u32_e32 v162, s3, v161
	v_add_lshl_u32 v0, v0, v14, 1
	v_add_u32_e32 v163, s8, v154
	v_readlane_b32 s8, v253, 25
	v_add_u32_e32 v164, s3, v163
	s_waitcnt vmcnt(6)
	v_lshl_add_u64 v[138:139], s[4:5], 0, v[0:1]
	v_add_u32_e32 v165, s8, v154
	v_readlane_b32 s8, v253, 26
	v_add_u32_e32 v166, s3, v165
	v_add_u32_e32 v0, v19, v16
	v_add_u32_e32 v167, s8, v154
	v_readlane_b32 s8, v253, 27
	v_add_u32_e32 v168, s3, v167
	v_add_lshl_u32 v0, v0, v18, 1
	v_add_u32_e32 v169, s8, v154
	v_readfirstlane_b32 s8, v3
	v_cvt_f32_u32_e32 v3, s25
	v_add_u32_e32 v170, s3, v169
	s_sub_i32 s3, 0, s56
	s_mul_i32 s3, s3, s8
	v_rcp_iflag_f32_e32 v3, v3
	s_mul_hi_u32 s3, s8, s3
	s_add_i32 s3, s8, s3
	v_writelane_b32 v254, s3, 33
	v_mul_f32_e32 v3, 0x4f7ffffe, v3
	v_cvt_u32_f32_e32 v3, v3
	s_sub_i32 s3, 0, s25
	v_bitop3_b32 v152, v22, s1, v17 bitop3:0xde
	s_mov_b32 s38, 0
	v_readfirstlane_b32 s8, v3
	s_mul_i32 s3, s3, s8
	s_mul_hi_u32 s3, s8, s3
	s_add_i32 s3, s8, s3
	v_cmp_eq_u32_e64 s[0:1], 0, v20
	s_and_b32 s41, s54, 7
	v_writelane_b32 v254, s3, 35
	v_lshl_add_u64 v[140:141], s[4:5], 0, v[0:1]
	v_add_u32_e32 v171, 0, v23
	v_lshlrev_b32_e32 v0, 1, v2
	s_barrier
	s_branch .LBB0_388

; #define PG8_STAGE(bufoff, gbase, voff) do { _Pragma("unroll") for (int _i = 0; _i < 2; ++_i) \
;         __builtin_amdgcn_global_load_lds((const unsigned*)((const char*)(gbase) + (voff)[_i]), (LAS unsigned*)(lds + (bufoff) + ldsw + _i * 8192), 16, 0, 0); } while (0)
; #define PG8_WAIT_V(n) asm volatile("s_waitcnt vmcnt(" #n ")" ::: "memory")
; #define PG8_BAR __builtin_amdgcn_s_barrier()
; template <class Epi>
; __device__ __forceinline__ void gemm_phase(LAS unsigned char* lds, const Gemm g, const Sched& S, const Epi& E) {
;     ...
;     PG8_STAGE(PG8_SB(0, 0), cB, voffB); PG8_STAGE(PG8_SA(0, 0), cA, voffA); PG8_STAGE(PG8_SB(0, 1), cB + hstepB, voffB); PG8_STAGE(PG8_SA(0, 1), cA + hstepA, voffA);
;     if (wr == 1) PG8_BAR;
;     PG8_WAIT_V(4); PG8_BAR;
;     PG8_STAGE(PG8_SB(1, 0), cB + kstep, voffB); PG8_STAGE(PG8_SA(1, 0), cA + kstep, voffA); PG8_STAGE(PG8_SB(1, 1), cB + hstepB + kstep, voffB);
;     PG8_WAIT_V(6); PG8_BAR;
.LBB0_449:
	s_add_i32 m0, s24, 0x18000
	v_lshl_add_u64 v[2:3], v[2:3], 0, s[60:61]
	global_load_lds_dwordx4 v[2:3], off
	v_lshl_add_u64 v[2:3], v[4:5], 0, s[60:61]
	s_add_i32 m0, s24, 0x1a000
	s_add_i32 s40, s24, 0x8000
	global_load_lds_dwordx4 v[2:3], off
	v_lshl_add_u64 v[2:3], v[6:7], 0, s[60:61]
	s_mov_b32 m0, s40
	s_add_i32 s41, s24, 0xa000
	global_load_lds_dwordx4 v[2:3], off
	v_lshl_add_u64 v[2:3], v[8:9], 0, s[60:61]
	s_mov_b32 m0, s41
	v_lshrrev_b32_e32 v22, 1, v15
	global_load_lds_dwordx4 v[2:3], off
	s_add_i32 m0, s24, 0x1c000
	v_lshl_add_u64 v[2:3], v[10:11], 0, s[60:61]
	global_load_lds_dwordx4 v[2:3], off
	v_lshl_add_u64 v[2:3], v[12:13], 0, s[60:61]
	s_add_i32 m0, s24, 0x1e000
	v_and_b32_e32 v22, 24, v22
	global_load_lds_dwordx4 v[2:3], off
	v_and_b32_e32 v21, 15, v15
	v_lshlrev_b32_e32 v23, 1, v22
	v_lshlrev_b32_e32 v15, 2, v15
	s_lshl_b32 s0, s0, 5
	v_lshl_or_b32 v210, s1, 6, v21
	v_lshl_or_b32 v21, v21, 6, v23
	s_lshl_b32 s1, s1, 13
	v_and_b32_e32 v15, 32, v15
	s_and_b32 s0, s0, 0x60
	v_bitop3_b32 v23, v21, s1, v15 bitop3:0xde
	s_lshl_b32 s1, s0, 7
	v_bitop3_b32 v211, v21, s1, v15 bitop3:0xde
	v_readlane_b32 s1, v254, 13
	v_readlane_b32 s8, v253, 30
	s_ashr_i32 s43, s1, 31
	v_readlane_b32 s1, v254, 5
	v_readlane_b32 s8, v254, 37
	s_mul_i32 s53, s1, s8
	v_cvt_f32_u32_e32 v2, s53
	v_or_b32_e32 v212, s0, v22
	s_sub_i32 s0, 0, s53
	v_mov_b32_e32 v3, v1
	v_rcp_iflag_f32_e32 v2, v2
	s_waitcnt vmcnt(6)
	v_readlane_b32 s9, v253, 31
	s_lshr_b32 s48, s54, 3
	v_mul_f32_e32 v2, 0x4f7ffffe, v2
	v_cvt_u32_f32_e32 v2, v2
	s_add_i32 s42, s73, -2
	s_mov_b32 s27, s9
	s_and_b32 s51, s54, 7
	v_readfirstlane_b32 s1, v2
	v_cvt_f32_u32_e32 v2, s25
	s_mul_i32 s0, s0, s1
	s_mul_hi_u32 s0, s1, s0
	s_add_i32 s58, s1, s0
	v_rcp_iflag_f32_e32 v2, v2
	s_sub_i32 s0, 0, s25
	s_add_i32 s52, s48, 1
	s_mov_b32 s56, 0
	v_mul_f32_e32 v2, 0x4f7ffffe, v2
	v_cvt_u32_f32_e32 v2, v2
	v_add_u32_e32 v213, 0, v23
	s_barrier
	v_readfirstlane_b32 s1, v2
	v_add_u32_e32 v2, v17, v14
	v_add_lshl_u32 v2, v2, v16, 1
	s_mul_i32 s0, s0, s1
	v_lshl_add_u64 v[202:203], s[36:37], 0, v[2:3]
	v_add_u32_e32 v2, v20, v18
	s_mul_hi_u32 s0, s1, s0
	v_add_lshl_u32 v2, v2, v19, 1
	s_add_i32 s64, s1, s0
	v_lshl_add_u64 v[204:205], s[36:37], 0, v[2:3]
	s_branch .LBB0_451

; #define PG8_STAGE(bufoff, gbase, voff) do { _Pragma("unroll") for (int _i = 0; _i < 2; ++_i) \
;         __builtin_amdgcn_global_load_lds((const unsigned*)((const char*)(gbase) + (voff)[_i]), (LAS unsigned*)(lds + (bufoff) + ldsw + _i * 8192), 16, 0, 0); } while (0)
; #define PG8_WAIT_V(n) asm volatile("s_waitcnt vmcnt(" #n ")" ::: "memory")
; #define PG8_BAR __builtin_amdgcn_s_barrier()
; template <class Epi>
; __device__ __forceinline__ void gemm_phase(LAS unsigned char* lds, const Gemm g, const Sched& S, const Epi& E) {
;     ...
;     PG8_STAGE(PG8_SB(0, 0), cB, voffB); PG8_STAGE(PG8_SA(0, 0), cA, voffA); PG8_STAGE(PG8_SB(0, 1), cB + hstepB, voffB); PG8_STAGE(PG8_SA(0, 1), cA + hstepA, voffA);
;     if (wr == 1) PG8_BAR;
;     PG8_WAIT_V(4); PG8_BAR;
;     PG8_STAGE(PG8_SB(1, 0), cB + kstep, voffB); PG8_STAGE(PG8_SA(1, 0), cA + kstep, voffA); PG8_STAGE(PG8_SB(1, 1), cB + hstepB + kstep, voffB);
;     PG8_WAIT_V(6); PG8_BAR;
.LBB0_541:
	s_add_i32 m0, s33, 0x18000
	v_lshl_add_u64 v[2:3], v[2:3], 0, s[60:61]
	global_load_lds_dwordx4 v[2:3], off
	v_lshl_add_u64 v[2:3], v[4:5], 0, s[60:61]
	s_add_i32 m0, s33, 0x1a000
	s_add_i32 s41, s33, 0x8000
	global_load_lds_dwordx4 v[2:3], off
	v_lshl_add_u64 v[2:3], v[6:7], 0, s[60:61]
	s_mov_b32 m0, s41
	s_add_i32 s42, s33, 0xa000
	global_load_lds_dwordx4 v[2:3], off
	v_lshl_add_u64 v[2:3], v[8:9], 0, s[60:61]
	s_mov_b32 m0, s42
	v_lshrrev_b32_e32 v21, 1, v16
	global_load_lds_dwordx4 v[2:3], off
	s_add_i32 m0, s33, 0x1c000
	v_lshl_add_u64 v[2:3], v[10:11], 0, s[60:61]
	global_load_lds_dwordx4 v[2:3], off
	v_lshl_add_u64 v[2:3], v[12:13], 0, s[60:61]
	s_add_i32 m0, s33, 0x1e000
	v_and_b32_e32 v21, 24, v21
	global_load_lds_dwordx4 v[2:3], off
	v_and_b32_e32 v154, 15, v16
	s_lshl_b32 s8, s1, 6
	v_lshlrev_b32_e32 v22, 1, v21
	v_lshlrev_b32_e32 v16, 2, v16
	s_lshl_b32 s0, s0, 5
	v_and_b32_e32 v2, 63, v219
	v_or_b32_e32 v155, s8, v154
	v_lshl_or_b32 v22, v154, 6, v22
	s_lshl_b32 s1, s1, 13
	v_and_b32_e32 v16, 32, v16
	s_and_b32 s0, s0, 0x60
	v_or_b32_e32 v157, s8, v2
	v_readlane_b32 s8, v253, 61
	v_bitop3_b32 v23, v22, s1, v16 bitop3:0xde
	s_lshl_b32 s1, s0, 7
	s_add_i32 s43, s73, -2
	v_readlane_b32 s9, v253, 62
	s_cmp_eq_u64 s[8:9], 0
	v_bitop3_b32 v156, v22, s1, v16 bitop3:0xde
	s_cselect_b64 s[78:79], -1, 0
	s_cmp_lg_u64 s[8:9], 0
	v_readlane_b32 s1, v254, 13
	s_cselect_b64 s[80:81], -1, 0
	s_ashr_i32 s48, s1, 31
	s_lshr_b32 s1, s54, 3
	v_writelane_b32 v254, s1, 33
	s_add_i32 s1, s1, 1
	v_readlane_b32 s8, v253, 30
	v_writelane_b32 v254, s1, 31
	v_or_b32_e32 v158, s0, v21
	v_readlane_b32 s1, v254, 5
	v_readlane_b32 s8, v254, 37
	s_mul_i32 s24, s1, s8
	v_cvt_f32_u32_e32 v2, s24
	s_sub_i32 s0, 0, s24
	v_mov_b32_e32 v3, v1
	s_waitcnt vmcnt(6)
	v_rcp_iflag_f32_e32 v2, v2
	v_readlane_b32 s9, v253, 31
	s_mov_b32 s27, s9
	s_and_b32 s52, s54, 7
	v_mul_f32_e32 v2, 0x4f7ffffe, v2
	v_cvt_u32_f32_e32 v2, v2
	s_mov_b32 s56, 0
	v_add_u32_e32 v159, 0, v23
	s_barrier
	v_readfirstlane_b32 s1, v2
	v_cvt_f32_u32_e32 v2, s25
	s_mul_i32 s0, s0, s1
	s_mul_hi_u32 s0, s1, s0
	s_add_i32 s58, s1, s0
	v_rcp_iflag_f32_e32 v2, v2
	s_sub_i32 s0, 0, s25
	v_mul_f32_e32 v2, 0x4f7ffffe, v2
	v_cvt_u32_f32_e32 v2, v2
	s_nop 0
	v_readfirstlane_b32 s1, v2
	v_add_u32_e32 v2, v17, v14
	v_add_lshl_u32 v2, v2, v15, 1
	s_mul_i32 s0, s0, s1
	v_lshl_add_u64 v[136:137], s[36:37], 0, v[2:3]
	v_add_u32_e32 v2, v20, v18
	s_mul_hi_u32 s0, s1, s0
	v_add_lshl_u32 v2, v2, v19, 1
	s_add_i32 s64, s1, s0
	v_lshl_add_u64 v[138:139], s[36:37], 0, v[2:3]
	s_branch .LBB0_543

; #define PG8_STAGE(bufoff, gbase, voff) do { _Pragma("unroll") for (int _i = 0; _i < 2; ++_i) \
;         __builtin_amdgcn_global_load_lds((const unsigned*)((const char*)(gbase) + (voff)[_i]), (LAS unsigned*)(lds + (bufoff) + ldsw + _i * 8192), 16, 0, 0); } while (0)
; #define PG8_WAIT_V(n) asm volatile("s_waitcnt vmcnt(" #n ")" ::: "memory")
; #define PG8_BAR __builtin_amdgcn_s_barrier()
; template <class Epi>
; __device__ __forceinline__ void gemm_phase(LAS unsigned char* lds, const Gemm g, const Sched& S, const Epi& E) {
;     ...
;     PG8_STAGE(PG8_SB(0, 0), cB, voffB); PG8_STAGE(PG8_SA(0, 0), cA, voffA); PG8_STAGE(PG8_SB(0, 1), cB + hstepB, voffB); PG8_STAGE(PG8_SA(0, 1), cA + hstepA, voffA);
;     if (wr == 1) PG8_BAR;
;     PG8_WAIT_V(4); PG8_BAR;
;     PG8_STAGE(PG8_SB(1, 0), cB + kstep, voffB); PG8_STAGE(PG8_SA(1, 0), cA + kstep, voffA); PG8_STAGE(PG8_SB(1, 1), cB + hstepB + kstep, voffB);
;     PG8_WAIT_V(6); PG8_BAR;
.LBB0_635:
	s_add_i32 m0, s89, 0x18000
	v_lshl_add_u64 v[2:3], v[2:3], 0, s[60:61]
	global_load_lds_dwordx4 v[2:3], off
	v_lshl_add_u64 v[2:3], v[4:5], 0, s[60:61]
	s_add_i32 m0, s89, 0x1a000
	s_add_i32 s93, s89, 0x8000
	global_load_lds_dwordx4 v[2:3], off
	v_lshl_add_u64 v[2:3], v[6:7], 0, s[60:61]
	s_mov_b32 m0, s93
	s_add_i32 s94, s89, 0xa000
	global_load_lds_dwordx4 v[2:3], off
	v_lshl_add_u64 v[2:3], v[8:9], 0, s[60:61]
	s_mov_b32 m0, s94
	v_lshrrev_b32_e32 v20, 1, v0
	global_load_lds_dwordx4 v[2:3], off
	s_add_i32 m0, s89, 0x1c000
	v_lshl_add_u64 v[2:3], v[10:11], 0, s[60:61]
	global_load_lds_dwordx4 v[2:3], off
	v_lshl_add_u64 v[2:3], v[12:13], 0, s[60:61]
	s_add_i32 m0, s89, 0x1e000
	v_and_b32_e32 v20, 24, v20
	global_load_lds_dwordx4 v[2:3], off
	v_and_b32_e32 v234, 15, v0
	v_lshlrev_b32_e32 v21, 1, v20
	v_lshlrev_b32_e32 v0, 2, v0
	s_and_b32 s8, s2, 3
	s_lshl_b32 s9, s14, 6
	v_lshl_or_b32 v21, v234, 6, v21
	s_lshl_b32 s14, s14, 13
	v_and_b32_e32 v0, 32, v0
	v_bitop3_b32 v22, v21, s14, v0 bitop3:0xde
	s_lshl_b32 s14, s8, 5
	s_lshl_b32 s8, s8, 12
	v_bitop3_b32 v236, v21, s8, v0 bitop3:0xde
	v_and_b32_e32 v0, 63, v219
	v_or_b32_e32 v235, s9, v234
	v_or_b32_e32 v237, s9, v0
	s_lshl_b32 s2, s2, 6
	v_readlane_b32 s8, v253, 61
	s_add_i32 s95, s73, -2
	s_and_b32 s2, s2, 0x80
	v_readlane_b32 s9, v253, 62
	s_cmp_eq_u64 s[8:9], 0
	s_cselect_b64 s[76:77], -1, 0
	s_cmp_lg_u64 s[8:9], 0
	v_readlane_b32 s8, v254, 13
	s_cselect_b64 s[78:79], -1, 0
	s_ashr_i32 s96, s8, 31
	s_lshr_b32 s8, s54, 3
	v_and_or_b32 v2, s14, 32, v20
	v_writelane_b32 v253, s8, 30
	s_add_i32 s65, s8, 1
	v_readlane_b32 s8, v254, 5
	v_readlane_b32 s9, v254, 37
	s_mul_i32 s97, s8, s9
	v_lshlrev_b32_e32 v0, 3, v2
	v_lshl_add_u64 v[186:187], s[84:85], 0, v[0:1]
	v_cvt_f32_u32_e32 v0, s97
	s_sub_i32 s8, 0, s97
	s_waitcnt vmcnt(6)
	v_or_b32_e32 v238, s14, v20
	v_rcp_iflag_f32_e32 v0, v0
	s_mov_b32 s27, s39
	s_and_b32 s71, s54, 7
	s_mov_b32 s67, s39
	v_mul_f32_e32 v0, 0x4f7ffffe, v0
	v_cvt_u32_f32_e32 v0, v0
	s_mov_b32 s42, 0
	v_add_u32_e32 v239, 0, v22
	s_lshl_b32 s66, s2, 1
	v_readfirstlane_b32 s9, v0
	v_cvt_f32_u32_e32 v0, s25
	s_mul_i32 s8, s8, s9
	s_mul_hi_u32 s8, s9, s8
	s_add_i32 s43, s9, s8
	v_rcp_iflag_f32_e32 v0, v0
	s_sub_i32 s8, 0, s25
	s_barrier
	v_mul_f32_e32 v0, 0x4f7ffffe, v0
	v_cvt_u32_f32_e32 v0, v0
	s_nop 0
	v_readfirstlane_b32 s9, v0
	v_add_u32_e32 v0, v16, v14
	v_add_lshl_u32 v0, v0, v15, 1
	s_mul_i32 s8, s8, s9
	v_lshl_add_u64 v[188:189], s[6:7], 0, v[0:1]
	v_add_u32_e32 v0, v19, v17
	s_mul_hi_u32 s8, s9, s8
	v_add_lshl_u32 v0, v0, v18, 1
	s_add_i32 s52, s9, s8
	v_lshl_add_u64 v[190:191], s[6:7], 0, v[0:1]
	v_lshlrev_b32_e32 v0, 1, v2
	s_branch .LBB0_637

; #define PG8_STAGE(bufoff, gbase, voff) do { _Pragma("unroll") for (int _i = 0; _i < 2; ++_i) \
;         __builtin_amdgcn_global_load_lds((const unsigned*)((const char*)(gbase) + (voff)[_i]), (LAS unsigned*)(lds + (bufoff) + ldsw + _i * 8192), 16, 0, 0); } while (0)
; #define PG8_WAIT_V(n) asm volatile("s_waitcnt vmcnt(" #n ")" ::: "memory")
; #define PG8_BAR __builtin_amdgcn_s_barrier()
; template <class Epi>
; __device__ __forceinline__ void gemm_phase(LAS unsigned char* lds, const Gemm g, const Sched& S, const Epi& E) {
;     ...
;     PG8_STAGE(PG8_SB(0, 0), cB, voffB); PG8_STAGE(PG8_SA(0, 0), cA, voffA); PG8_STAGE(PG8_SB(0, 1), cB + hstepB, voffB); PG8_STAGE(PG8_SA(0, 1), cA + hstepA, voffA);
;     if (wr == 1) PG8_BAR;
;     PG8_WAIT_V(4); PG8_BAR;
;     PG8_STAGE(PG8_SB(1, 0), cB + kstep, voffB); PG8_STAGE(PG8_SA(1, 0), cA + kstep, voffA); PG8_STAGE(PG8_SB(1, 1), cB + hstepB + kstep, voffB);
;     PG8_WAIT_V(6); PG8_BAR;
.LBB0_706:
	v_bfe_u32 v21, v16, 4, 2
	v_and_b32_e32 v22, 15, v16
	v_lshlrev_b32_e32 v23, 4, v21
	v_lshlrev_b32_e32 v16, 2, v16
	v_lshl_or_b32 v216, s2, 6, v22
	v_lshl_or_b32 v22, v22, 6, v23
	s_lshl_b32 s2, s2, 13
	v_and_b32_e32 v16, 32, v16
	v_bitop3_b32 v23, v22, s2, v16 bitop3:0xde
	s_lshl_b32 s2, s3, 5
	s_and_b32 s3, s2, 0x60
	s_add_i32 m0, s52, 0x18000
	v_lshl_add_u64 v[2:3], v[2:3], 0, s[60:61]
	s_lshl_b32 s2, s3, 7
	global_load_lds_dwordx4 v[2:3], off
	v_lshl_add_u64 v[2:3], v[4:5], 0, s[60:61]
	s_add_i32 m0, s52, 0x1a000
	s_add_i32 s51, s52, 0x8000
	v_bitop3_b32 v217, v22, s2, v16 bitop3:0xde
	global_load_lds_dwordx4 v[2:3], off
	v_lshl_add_u64 v[2:3], v[6:7], 0, s[60:61]
	s_mov_b32 m0, s51
	s_add_i32 s2, s52, 0xa000
	global_load_lds_dwordx4 v[2:3], off
	v_lshl_add_u64 v[2:3], v[8:9], 0, s[60:61]
	s_mov_b32 m0, s2
	v_readlane_b32 s8, v254, 13
	global_load_lds_dwordx4 v[2:3], off
	s_add_i32 m0, s52, 0x1c000
	v_lshl_add_u64 v[2:3], v[10:11], 0, s[60:61]
	global_load_lds_dwordx4 v[2:3], off
	v_lshl_add_u64 v[2:3], v[12:13], 0, s[60:61]
	s_add_i32 m0, s52, 0x1e000
	s_ashr_i32 s72, s8, 31
	global_load_lds_dwordx4 v[2:3], off
	v_readlane_b32 s8, v253, 30
	s_lshr_b32 s8, s54, 3
	v_readlane_b32 s9, v253, 31
	v_writelane_b32 v254, s8, 33
	s_add_i32 s8, s8, 1
	v_writelane_b32 v254, s8, 9
	s_mov_b32 s27, s9
	v_readlane_b32 s8, v254, 5
	s_mul_i32 s58, s8, s57
	v_cvt_f32_u32_e32 v2, s58
	v_writelane_b32 v254, s57, 37
	s_add_i32 s48, s73, -2
	v_readlane_b32 s8, v254, 7
	v_rcp_iflag_f32_e32 v2, v2
	s_and_b32 s64, s54, 7
	v_readlane_b32 s9, v254, 8
	s_cmp_eq_u64 s[8:9], 0
	v_mul_f32_e32 v2, 0x4f7ffffe, v2
	v_cvt_u32_f32_e32 v2, v2
	s_cselect_b64 s[36:37], -1, 0
	s_cmp_lg_u64 s[8:9], 0
	v_readlane_b32 s8, v254, 1
	v_readfirstlane_b32 s14, v2
	v_cvt_f32_u32_e32 v2, s25
	s_cselect_b64 s[78:79], -1, 0
	s_cmp_lg_u64 s[68:69], 0
	v_readlane_b32 s9, v254, 2
	v_rcp_iflag_f32_e32 v2, v2
	s_cselect_b64 s[82:83], -1, 0
	s_cmp_lg_u64 s[8:9], 0
	s_cselect_b64 s[84:85], -1, 0
	v_mul_f32_e32 v2, 0x4f7ffffe, v2
	v_lshl_or_b32 v234, v21, 3, s3
	s_sub_i32 s3, 0, s58
	v_cvt_u32_f32_e32 v2, v2
	s_mul_i32 s3, s3, s14
	s_mul_hi_u32 s3, s14, s3
	s_add_i32 s3, s14, s3
	v_writelane_b32 v254, s3, 29
	s_sub_i32 s3, 0, s25
	v_readfirstlane_b32 s14, v2
	v_add_u32_e32 v2, v17, v14
	s_mul_i32 s3, s3, s14
	v_add_lshl_u32 v2, v2, v15, 1
	v_mov_b32_e32 v3, v1
	s_waitcnt vmcnt(6)
	s_mul_hi_u32 s3, s14, s3
	v_lshl_add_u64 v[202:203], s[40:41], 0, v[2:3]
	v_add_u32_e32 v2, v20, v18
	s_add_i32 s3, s14, s3
	v_add_lshl_u32 v2, v2, v19, 1
	s_mov_b32 s33, 0
	v_cmp_eq_u32_e64 s[6:7], 0, v21
	s_mov_b32 s71, s70
	s_mov_b32 s80, s70
	s_mov_b32 s81, s70
	v_writelane_b32 v254, s3, 31
	v_lshl_add_u64 v[204:205], s[40:41], 0, v[2:3]
	v_add_u32_e32 v235, 0, v23
	s_barrier
	s_branch .LBB0_709

; #define PG8_STAGE(bufoff, gbase, voff) do { _Pragma("unroll") for (int _i = 0; _i < 2; ++_i) \
;         __builtin_amdgcn_global_load_lds((const unsigned*)((const char*)(gbase) + (voff)[_i]), (LAS unsigned*)(lds + (bufoff) + ldsw + _i * 8192), 16, 0, 0); } while (0)
; #define PG8_WAIT_V(n) asm volatile("s_waitcnt vmcnt(" #n ")" ::: "memory")
; #define PG8_BAR __builtin_amdgcn_s_barrier()
; template <class Epi>
; __device__ __forceinline__ void gemm_phase(LAS unsigned char* lds, const Gemm g, const Sched& S, const Epi& E) {
;     ...
;     PG8_STAGE(PG8_SB(0, 0), cB, voffB); PG8_STAGE(PG8_SA(0, 0), cA, voffA); PG8_STAGE(PG8_SB(0, 1), cB + hstepB, voffB); PG8_STAGE(PG8_SA(0, 1), cA + hstepA, voffA);
;     if (wr == 1) PG8_BAR;
;     PG8_WAIT_V(4); PG8_BAR;
;     PG8_STAGE(PG8_SB(1, 0), cB + kstep, voffB); PG8_STAGE(PG8_SA(1, 0), cA + kstep, voffA); PG8_STAGE(PG8_SB(1, 1), cB + hstepB + kstep, voffB);
;     PG8_WAIT_V(6); PG8_BAR;
.LBB0_812:
	s_add_i32 m0, s33, 0x18000
	v_lshl_add_u64 v[2:3], v[2:3], 0, s[60:61]
	global_load_lds_dwordx4 v[2:3], off
	v_lshl_add_u64 v[2:3], v[4:5], 0, s[60:61]
	s_add_i32 m0, s33, 0x1a000
	s_add_i32 s75, s33, 0x8000
	global_load_lds_dwordx4 v[2:3], off
	v_lshl_add_u64 v[2:3], v[6:7], 0, s[60:61]
	s_mov_b32 m0, s75
	s_add_i32 s76, s33, 0xa000
	global_load_lds_dwordx4 v[2:3], off
	v_lshl_add_u64 v[2:3], v[8:9], 0, s[60:61]
	s_mov_b32 m0, s76
	s_sext_i32_i16 s55, s0
	global_load_lds_dwordx4 v[2:3], off
	s_add_i32 m0, s33, 0x1c000
	v_lshl_add_u64 v[2:3], v[10:11], 0, s[60:61]
	global_load_lds_dwordx4 v[2:3], off
	v_lshl_add_u64 v[2:3], v[12:13], 0, s[60:61]
	s_add_i32 m0, s33, 0x1e000
	s_lshl_b32 s0, s24, 6
	global_load_lds_dwordx4 v[2:3], off
	v_and_b32_e32 v2, 63, v219
	v_or_b32_e32 v147, s0, v2
	v_cvt_f32_u32_e32 v2, s74
	v_lshrrev_b32_e32 v21, 1, v20
	v_and_b32_e32 v21, 24, v21
	v_and_b32_e32 v141, 15, v20
	v_rcp_iflag_f32_e32 v2, v2
	v_lshlrev_b32_e32 v22, 1, v21
	v_lshlrev_b32_e32 v20, 2, v20
	s_lshl_b32 s1, s1, 5
	v_mul_f32_e32 v2, 0x4f7ffffe, v2
	v_cvt_u32_f32_e32 v2, v2
	v_lshl_or_b32 v22, v141, 6, v22
	s_lshl_b32 s24, s24, 13
	v_and_b32_e32 v20, 32, v20
	s_and_b32 s1, s1, 0x60
	v_readlane_b32 s36, v253, 61
	v_bitop3_b32 v23, v22, s24, v20 bitop3:0xde
	s_lshl_b32 s24, s1, 7
	s_add_i32 s77, s73, -2
	v_readlane_b32 s37, v253, 62
	s_cmp_eq_u64 s[36:37], 0
	s_cselect_b64 s[34:35], -1, 0
	s_cmp_lg_u64 s[36:37], 0
	v_or_b32_e32 v149, s1, v21
	v_readfirstlane_b32 s1, v2
	v_add_u32_e32 v2, v16, v14
	v_or_b32_e32 v143, s0, v141
	s_cselect_b64 s[36:37], -1, 0
	s_sub_i32 s0, 0, s74
	v_add_lshl_u32 v2, v2, v15, 1
	v_mov_b32_e32 v3, v1
	s_waitcnt vmcnt(6)
	s_mul_i32 s0, s0, s1
	v_lshl_add_u64 v[136:137], s[6:7], 0, v[2:3]
	v_add_u32_e32 v2, v19, v17
	s_mul_hi_u32 s0, s1, s0
	v_add_lshl_u32 v2, v2, v18, 1
	v_bitop3_b32 v145, v22, s24, v20 bitop3:0xde
	s_mov_b32 s27, s9
	s_mov_b32 s24, 0
	s_add_i32 s78, s1, s0
	v_lshl_add_u64 v[138:139], s[6:7], 0, v[2:3]
	v_add_u32_e32 v151, 0, v23
	s_barrier
